# site 9 (out-GEMM to FFN2 up-GEMM) back to the full grid barrier: act aliases Yg/ycat/PV across batches, XCD-local barriers alone let a fast XCD overwrite ycat another XCD still reads; P0 weight items
# baseline (speedup 1.0000x reference)
; __global__ void __launch_bounds__(512, 2) fwd_megakernel(Args args) {
;     ...
;         for (int mi = 0; mi < 12; ++mi) {
;             const int l = mi / 6, t = mi % 6;
;             const float* g; const float* u = nullptr; const float* ks = nullptr; int kind = 0, ldn, K, Np; bf16* WT = (bf16*)(ws + WS_W + (size_t)l * WL_SIZE);
;             if (t == 0)      { g = args.in[2] + (size_t)l * DM * DFF; u = args.in[3] + (size_t)l * DM * DFF; ks = args.in[1] + l * DM; kind = 1; ldn = DFF; K = DM; Np = NGU; WT += WL_GU1 / 2; }
;             else if (t == 1) { g = args.in[4] + (size_t)l * DFF * DM; ldn = DM; K = DFF; Np = DM; WT += WL_D1 / 2; }
;             else if (t == 2) { g = args.in[6] + (size_t)l * DM * DINP; ks = args.in[5] + l * DM; kind = 2; ldn = DINP; K = DM; Np = NPROJ; WT += WL_IN / 2; }
;             else if (t == 3) { g = args.in[21] + (size_t)l * DM * DM; ldn = DM; K = DM; Np = DM; WT += WL_OUT / 2; }
;             else if (t == 4) { g = args.in[23] + (size_t)l * DM * DFF; u = args.in[24] + (size_t)l * DM * DFF; ks = args.in[22] + l * DM; kind = 1; ldn = DFF; K = DM; Np = NGU; WT += WL_GU2 / 2; }
;             else             { g = args.in[25] + (size_t)l * DFF * DM; ldn = DM; K = DFF; Np = DM; WT += WL_D2 / 2; }
;             const int nitems = (K / 64) * (Np / 32);
;             for (int it = gw; it < nitems; it += NGW) transpose_item(kind, g, u, ldn, K, Np, ks, WT, scr, it, lane);
.LBB0_36:
	s_lshr_b32 s84, s79, 6
	s_mul_i32 s84, s84, s77
	v_readlane_b32 s6, v251, 61
	s_cmp_gt_u32 s75, 5
	s_cselect_b32 s7, 0x80, 0
	s_cselect_b32 s32, 6, 0
	s_sub_u32 s32, s75, s32
	s_lshl_b32 s32, s32, 2
	s_lshr_b32 s32, 0x60c160, s32
	s_and_b32 s32, s32, 15
	s_lshl_b32 s32, s32, 7
	s_add_u32 s7, s7, s32
	s_sub_u32 s7, s6, s7
	s_and_b32 s7, s7, 0x7ff
	s_cmpk_lg_u32 s82, 0x100
	s_cselect_b32 s6, s6, s7
	v_writelane_b32 v255, s6, 41
	s_cmp_ge_i32 s6, s84
	v_readlane_b32 s7, v251, 62
	s_cbranch_scc1 .LBB0_20
	v_cvt_f32_u32_e32 v0, s77
	s_lshl_b32 s0, s78, 1
	s_lshl_b32 s6, s78, 2
	s_lshl_b32 s10, s78, 3
	v_rcp_iflag_f32_e32 v0, v0
	s_lshl_b32 s18, s78, 4
	s_lshl_b32 s36, s78, 5
	s_cmp_lg_u64 s[72:73], 0
	v_mul_f32_e32 v0, 0x4f7ffffe, v0
	v_cvt_u32_f32_e32 v0, v0
	v_mov_b32_e32 v13, v9
	s_cselect_b64 s[68:69], -1, 0
	v_lshl_add_u64 v[16:17], s[70:71], 0, v[12:13]
	s_sub_i32 s70, 0, s77
	v_readfirstlane_b32 s71, v0
	s_mul_i32 s70, s70, s71
	s_mul_hi_u32 s70, s71, s70
	s_add_i32 s85, s71, s70
	s_lshl_b32 s70, s77, 5
	s_sub_i32 s86, 0, s70
	v_readlane_b32 s70, v255, 41
	v_mov_b32_e32 v11, v9
	v_readlane_b32 s71, v251, 62
	v_lshl_add_u64 v[14:15], s[72:73], 0, v[10:11]
	s_mov_b32 s72, s70
	s_lshl_b32 s87, s70, 5
	v_readlane_b32 s71, v251, 63
	s_lshl_b32 s70, s77, 4
	s_mov_b32 s7, s1
	s_mul_i32 s8, s78, 6
	s_mov_b32 s9, s1
	s_mov_b32 s11, s1
	s_mul_i32 s12, s78, 10
	s_mov_b32 s13, s1
	s_mul_i32 s14, s78, 12
	s_mov_b32 s15, s1
	s_mul_i32 s16, s78, 14
	s_mov_b32 s17, s1
	s_mov_b32 s19, s1
	s_mul_i32 s20, s78, 18
	s_mov_b32 s21, s1
	s_mul_i32 s22, s78, 20
	s_mov_b32 s23, s1
	s_mul_i32 s24, s78, 22
	s_mov_b32 s25, s1
	s_mul_i32 s26, s78, 24
	s_mov_b32 s27, s1
	s_mul_i32 s28, s78, 26
	s_mov_b32 s29, s1
	s_mul_i32 s30, s78, 28
	s_mov_b32 s31, s1
	s_mul_i32 s34, s78, 30
	s_mov_b32 s35, s1
	s_mov_b32 s37, s1
	s_mul_i32 s38, s78, 34
	s_mov_b32 s39, s1
	s_mul_i32 s40, s78, 36
	s_mov_b32 s41, s1
	s_mul_i32 s42, s78, 38
	s_mov_b32 s43, s1
	s_mul_i32 s44, s78, 40
	s_mov_b32 s45, s1
	s_mul_i32 s46, s78, 42
	s_mov_b32 s47, s1
	s_mul_i32 s48, s78, 44
	s_mov_b32 s49, s1
	s_mul_i32 s50, s78, 46
	s_mov_b32 s51, s1
	s_mul_i32 s52, s78, 48
	s_mov_b32 s53, s1
	s_mul_i32 s54, s78, 50
	s_mov_b32 s55, s1
	s_mul_i32 s56, s78, 52
	s_mov_b32 s57, s1
	s_mul_i32 s58, s78, 54
	s_mov_b32 s59, s1
	s_mul_i32 s60, s78, 56
	s_mov_b32 s61, s1
	s_mul_i32 s62, s78, 58
	s_mov_b32 s63, s1
	s_mul_i32 s64, s78, 60
	s_mov_b32 s65, s1
	s_mul_i32 s66, s78, 62
	s_mov_b32 s67, s1
	s_lshl_b32 s88, s71, 5
	s_sub_i32 s89, 0, s70
	s_lshl_b32 s90, s72, 4
	s_lshl_b32 s91, s71, 4
	s_mov_b32 s92, s72
	s_branch .LBB0_41
